# v94 + write-after-read guard: all workgroups' attention counted on a global word, checked once before the SwiGLU GEMM whose output aliases the buffer the attention reads
# baseline (speedup 1.0000x reference)
; DI void grid_barrier(unsigned* cnt, unsigned target) {
;     asm volatile("s_waitcnt vmcnt(0) lgkmcnt(0)" ::: "memory");
;     __syncthreads();
;     if (threadIdx.x == 0) {
;         __builtin_amdgcn_fence(__ATOMIC_RELEASE, "agent");
;         asm volatile("s_waitcnt vmcnt(0)" ::: "memory");
;         __hip_atomic_fetch_add(cnt, 1u, __ATOMIC_RELAXED, __HIP_MEMORY_SCOPE_AGENT);
;         while (__hip_atomic_load(cnt, __ATOMIC_RELAXED, __HIP_MEMORY_SCOPE_AGENT) < target) __builtin_amdgcn_s_sleep(2);
;         __builtin_amdgcn_fence(__ATOMIC_ACQUIRE, "agent");
;         asm volatile("s_waitcnt vmcnt(0)" ::: "memory");
;     }
;     __syncthreads();
; }
; __global__ void __launch_bounds__(512, 2) fwd_megakernel(Args args) {
;     ...
;             } else if (type == T_SWI) {
;                 const int fi = l * 2 + (op == 1 ? 0 : 1);
;                 pg8::Gemm g{H, WSP(bf16_t, WS_WGU) + (size_t)fi * 2 * DFF * DM, DM, DM, DM, 0, 0}; pg8::Order S; S.init(nMt, 2 * DFF / 256, 1, F.G, bx);
;                 pg8::EpiSwiGLU E{BIG};
; #pragma unroll 1
;                 for (int rep_ = 0; rep_ < ((REP & 4) ? 2 : 1); ++rep_) pg8::gemm_phase(F.lds, F.tid, g, S, E);
.Ll3_mid:
	s_cmp_eq_u32 s98, 6
	s_cbranch_scc0 .Lwg_skip2
	v_readlane_b32 s10, v255, 63
	s_lshl_b32 s10, s10, 8
	s_mov_b64 s[4:5], exec
	v_readlane_b32 s6, v255, 3
	v_readlane_b32 s7, v255, 4
	s_and_b64 s[6:7], s[4:5], s[6:7]
	s_mov_b64 exec, s[6:7]
	s_cbranch_execz .Lwd_G2
.Lwp_G2:
	global_load_dword v0, v1, s[14:15] offset:200 sc1
	s_waitcnt vmcnt(0)
	v_cmp_gt_u32_e32 vcc, s10, v0
	s_cbranch_vccz .Lwd_G2
	s_sleep 2
	s_branch .Lwp_G2
.Lwd_G2:
	s_mov_b64 exec, s[4:5]
	s_barrier
.Lwg_skip2:
	s_waitcnt vmcnt(0) lgkmcnt(0)
	s_barrier
	v_readlane_b32 s10, v255, 60
	s_add_u32 s10, s10, 1
	s_nop 0
	v_writelane_b32 v255, s10, 60
	s_lshl_b32 s10, s10, 5
	v_readlane_b32 s2, v255, 0
	s_mov_b64 s[4:5], exec
	v_readlane_b32 s6, v255, 3
	v_readlane_b32 s7, v255, 4
	s_and_b64 s[6:7], s[4:5], s[6:7]
	s_mov_b64 exec, s[6:7]
	s_cbranch_execz .Llb_L3m
	s_and_b32 s3, s2, 7
	s_lshl_b32 s3, s3, 2
	s_add_u32 s8, s14, s3
	s_addc_u32 s9, s15, 0
	v_mov_b32_e32 v0, 1
	global_atomic_add v1, v0, s[8:9] offset:128

; DI void grid_barrier(unsigned* cnt, unsigned target) {
;     asm volatile("s_waitcnt vmcnt(0) lgkmcnt(0)" ::: "memory");
;     __syncthreads();
;     if (threadIdx.x == 0) {
;         __builtin_amdgcn_fence(__ATOMIC_RELEASE, "agent");
;         asm volatile("s_waitcnt vmcnt(0)" ::: "memory");
;         __hip_atomic_fetch_add(cnt, 1u, __ATOMIC_RELAXED, __HIP_MEMORY_SCOPE_AGENT);
;         while (__hip_atomic_load(cnt, __ATOMIC_RELAXED, __HIP_MEMORY_SCOPE_AGENT) < target) __builtin_amdgcn_s_sleep(2);
;         __builtin_amdgcn_fence(__ATOMIC_ACQUIRE, "agent");
;         asm volatile("s_waitcnt vmcnt(0)" ::: "memory");
;     }
;     __syncthreads();
; }
.Lch_start:
	s_cmp_eq_u32 s44, 11
	s_cbranch_scc0 .Lwg_skip1
	v_readlane_b32 s10, v255, 63
	s_lshl_b32 s10, s10, 8
	s_mov_b64 s[4:5], exec
	v_readlane_b32 s6, v255, 3
	v_readlane_b32 s7, v255, 4
	s_and_b64 s[6:7], s[4:5], s[6:7]
	s_mov_b64 exec, s[6:7]
	s_cbranch_execz .Lwd_G1

; DI void grid_barrier(unsigned* cnt, unsigned target) {
;     asm volatile("s_waitcnt vmcnt(0) lgkmcnt(0)" ::: "memory");
;     __syncthreads();
;     if (threadIdx.x == 0) {
;         __builtin_amdgcn_fence(__ATOMIC_RELEASE, "agent");
;         asm volatile("s_waitcnt vmcnt(0)" ::: "memory");
;         __hip_atomic_fetch_add(cnt, 1u, __ATOMIC_RELAXED, __HIP_MEMORY_SCOPE_AGENT);
;         while (__hip_atomic_load(cnt, __ATOMIC_RELAXED, __HIP_MEMORY_SCOPE_AGENT) < target) __builtin_amdgcn_s_sleep(2);
;         __builtin_amdgcn_fence(__ATOMIC_ACQUIRE, "agent");
;         asm volatile("s_waitcnt vmcnt(0)" ::: "memory");
;     }
;     __syncthreads();
; }
.Lwd_G1:
	s_mov_b64 exec, s[4:5]
	s_barrier
.Lwg_skip1:
	s_waitcnt vmcnt(0) lgkmcnt(0)
	s_barrier
	v_readlane_b32 s10, v255, 61
	s_add_u32 s10, s10, 1
	s_nop 0
	v_writelane_b32 v255, s10, 61
	s_mov_b64 s[4:5], exec
	v_readlane_b32 s6, v255, 3
	v_readlane_b32 s7, v255, 4
	s_and_b64 s[6:7], s[4:5], s[6:7]
	s_mov_b64 exec, s[6:7]
	s_cbranch_execz .Lar_C
	buffer_wbl2 sc1
	s_waitcnt vmcnt(0)
	v_mov_b32_e32 v0, 1
	v_readlane_b32 s2, v255, 0
	s_bfe_u32 s2, s2, 0x20001
	s_lshl_b32 s2, s2, 2
	s_add_u32 s8, s14, s2
	s_addc_u32 s9, s15, 0
	global_atomic_add v1, v0, s[8:9] offset:160

; DI const float* in_ptr(const Args& AR, int i) { asm volatile("" : "+s"(i)); return GLOBAL_PTR(const float, AR.in[i]); }
; #define GRID_SYNC() do { nbar += (unsigned)gridDim.x; grid_barrier(barw, nbar); } while (0)
; __global__ void __launch_bounds__(512, 2) fwd_megakernel(Args args) {
;     ...
;             } else if (type == T_ATTE) {
;                 if (PM & 1024) { const float* qg_ = in_ptr(AR, 11) + li * 128; attn_even_lds(F, in_ptr(AR, 12) + (size_t)li * 12 * 465, qg_ + 64, qg_); attn_evenctx_lds(F, qg_ + 64, qg_); }
;             } else if (type == T_ATTO) {
;                 if (PM & 2048) { const float* qg_ = in_ptr(AR, 15) + li * 128; attn_odd_lds(F, qg_ + 64, qg_, l < 3); }
;             }
;             if (!(op == 4 || op == 6 || op == 7 || skip0)) GRID_SYNC();
.Lxl_pre:
	s_waitcnt lgkmcnt(0)
	s_cmp_eq_u32 s13, 0x100
	s_cbranch_scc0 .Lxl_no
	s_cmp_eq_u32 s44, 9
	s_cbranch_scc0 .Lat_not9
	s_waitcnt vmcnt(0) lgkmcnt(0)
	s_barrier
	v_readlane_b32 s10, v255, 63
	s_add_u32 s10, s10, 1
	s_nop 0
	v_writelane_b32 v255, s10, 63
	s_mov_b64 s[4:5], exec
	v_readlane_b32 s6, v255, 3
	v_readlane_b32 s7, v255, 4
	s_and_b64 s[6:7], s[4:5], s[6:7]
	s_mov_b64 exec, s[6:7]
	s_cbranch_execz .Lar_E
	buffer_wbl2 sc1
	s_waitcnt vmcnt(0)
	v_mov_b32_e32 v0, 1
	v_readlane_b32 s2, v255, 0
	s_and_b32 s2, s2, 7
	s_lshl_b32 s2, s2, 2
	s_add_u32 s8, s14, s2
	s_addc_u32 s9, s15, 0
	global_atomic_add v1, v0, s[8:9] offset:208
	global_atomic_add v1, v0, s[14:15] offset:200
